# adds: RS skinny tasks issue both row-0 loads up front; RS GEMM prologues defer the first row-rstd wait past the first K-tile DMA issue; s3 MFMA sections batch their LDS fragment reads (counted lgkmcnt
# baseline (speedup 1.0000x reference)
.LBB0_266:
	s_or_b64 exec, exec, s[28:29]
	s_waitcnt lgkmcnt(0)
	s_barrier
	ds_read_b128 v[154:157], v109
	ds_read_b128 v[170:173], v142
	ds_read_b128 v[174:177], v142 offset:4352
	ds_read_b128 v[178:181], v142 offset:8704
	ds_read_b128 v[182:185], v142 offset:13056
	ds_read_b128 v[158:161], v109 offset:64
	ds_read_b128 v[186:189], v142 offset:64
	ds_read_b128 v[190:193], v142 offset:4416
	ds_read_b128 v[196:199], v142 offset:8768
	ds_read_b128 v[202:205], v142 offset:13120
	v_mul_f32_e32 v0, 0x3fb8aa3b, v0
	v_exp_f32_e32 v0, v0
	s_waitcnt lgkmcnt(5)
	v_mfma_f32_16x16x32_bf16 v[104:107], v[170:173], v[154:157], 0
	v_mfma_f32_16x16x32_bf16 v[100:103], v[174:177], v[154:157], 0
	v_mfma_f32_16x16x32_bf16 v[96:99], v[178:181], v[154:157], 0
	v_mfma_f32_16x16x32_bf16 v[92:95], v[182:185], v[154:157], 0
	ds_read_b128 v[162:165], v109 offset:128
	ds_read_b128 v[206:209], v142 offset:128
	ds_read_b128 v[210:213], v142 offset:4480
	ds_read_b128 v[214:217], v142 offset:8832
	ds_read_b128 v[218:221], v142 offset:13184
	s_waitcnt lgkmcnt(5)
	v_mfma_f32_16x16x32_bf16 v[104:107], v[186:189], v[158:161], v[104:107]
	v_mfma_f32_16x16x32_bf16 v[100:103], v[190:193], v[158:161], v[100:103]
	v_mfma_f32_16x16x32_bf16 v[96:99], v[196:199], v[158:161], v[96:99]
	v_mfma_f32_16x16x32_bf16 v[92:95], v[202:205], v[158:161], v[92:95]
	ds_read_b128 v[166:169], v109 offset:192
	ds_read_b128 v[222:225], v142 offset:192
	ds_read_b128 v[226:229], v142 offset:4544
	ds_read_b128 v[230:233], v142 offset:8896
	ds_read_b128 v[234:237], v142 offset:13248
	s_waitcnt lgkmcnt(5)
	v_mfma_f32_16x16x32_bf16 v[104:107], v[206:209], v[162:165], v[104:107]
	v_mfma_f32_16x16x32_bf16 v[100:103], v[210:213], v[162:165], v[100:103]
	v_mfma_f32_16x16x32_bf16 v[96:99], v[214:217], v[162:165], v[96:99]
	v_mfma_f32_16x16x32_bf16 v[92:95], v[218:221], v[162:165], v[92:95]
	s_waitcnt lgkmcnt(0)
	v_mfma_f32_16x16x32_bf16 v[104:107], v[222:225], v[166:169], v[104:107]
	v_mfma_f32_16x16x32_bf16 v[100:103], v[226:229], v[166:169], v[100:103]
	v_mfma_f32_16x16x32_bf16 v[96:99], v[230:233], v[166:169], v[96:99]
	v_mfma_f32_16x16x32_bf16 v[92:95], v[234:237], v[166:169], v[92:95]
	s_nop 7
	v_pk_mul_f32 v[104:105], v[0:1], v[104:105] op_sel_hi:[0,1]
	v_pk_mul_f32 v[106:107], v[0:1], v[106:107] op_sel_hi:[0,1]
	v_pk_mul_f32 v[100:101], v[0:1], v[100:101] op_sel_hi:[0,1]
	v_pk_mul_f32 v[102:103], v[0:1], v[102:103] op_sel_hi:[0,1]
	v_pk_mul_f32 v[96:97], v[0:1], v[96:97] op_sel_hi:[0,1]
	v_pk_mul_f32 v[98:99], v[0:1], v[98:99] op_sel_hi:[0,1]
	v_pk_mul_f32 v[92:93], v[0:1], v[92:93] op_sel_hi:[0,1]
	v_pk_mul_f32 v[94:95], v[0:1], v[94:95] op_sel_hi:[0,1]
	v_add_u32_e32 v0, v133, v121
	s_and_saveexec_b64 s[28:29], vcc
	s_cbranch_execnz .LBB0_273
	s_or_b64 exec, exec, s[28:29]
	s_and_saveexec_b64 s[28:29], s[4:5]
	s_cbranch_execnz .LBB0_274

.LBB0_270:
	ds_read_b128 v[154:157], v0 offset:35008
	ds_read_b128 v[170:173], v143 offset:192
	ds_read_b128 v[174:177], v143 offset:4544
	ds_read_b128 v[178:181], v143 offset:8896
	ds_read_b128 v[182:185], v143 offset:13248
	s_waitcnt lgkmcnt(3)
	v_mfma_f32_16x16x32_bf16 v[104:107], v[170:173], v[154:157], v[104:107]
	s_waitcnt lgkmcnt(2)
	v_mfma_f32_16x16x32_bf16 v[100:103], v[174:177], v[154:157], v[100:103]
	s_waitcnt lgkmcnt(1)
	v_mfma_f32_16x16x32_bf16 v[96:99], v[178:181], v[154:157], v[96:99]
	s_waitcnt lgkmcnt(0)
	v_mfma_f32_16x16x32_bf16 v[92:95], v[182:185], v[154:157], v[92:95]

.LBB0_273:
	ds_read_b128 v[154:157], v0 offset:34816
	ds_read_b128 v[170:173], v143
	ds_read_b128 v[174:177], v143 offset:4352
	ds_read_b128 v[178:181], v143 offset:8704
	ds_read_b128 v[182:185], v143 offset:13056
	s_waitcnt lgkmcnt(3)
	v_mfma_f32_16x16x32_bf16 v[104:107], v[170:173], v[154:157], v[104:107]
	s_waitcnt lgkmcnt(2)
	v_mfma_f32_16x16x32_bf16 v[100:103], v[174:177], v[154:157], v[100:103]
	s_waitcnt lgkmcnt(1)
	v_mfma_f32_16x16x32_bf16 v[96:99], v[178:181], v[154:157], v[96:99]
	s_waitcnt lgkmcnt(0)
	v_mfma_f32_16x16x32_bf16 v[92:95], v[182:185], v[154:157], v[92:95]
	s_or_b64 exec, exec, s[28:29]
	s_and_saveexec_b64 s[28:29], s[4:5]
	s_cbranch_execz .LBB0_268
.LBB0_274:
	ds_read_b128 v[154:157], v0 offset:34880
	ds_read_b128 v[170:173], v143 offset:64
	ds_read_b128 v[174:177], v143 offset:4416
	ds_read_b128 v[178:181], v143 offset:8768
	ds_read_b128 v[182:185], v143 offset:13120
	s_waitcnt lgkmcnt(3)
	v_mfma_f32_16x16x32_bf16 v[104:107], v[170:173], v[154:157], v[104:107]
	s_waitcnt lgkmcnt(2)
	v_mfma_f32_16x16x32_bf16 v[100:103], v[174:177], v[154:157], v[100:103]
	s_waitcnt lgkmcnt(1)
	v_mfma_f32_16x16x32_bf16 v[96:99], v[178:181], v[154:157], v[96:99]
	s_waitcnt lgkmcnt(0)
	v_mfma_f32_16x16x32_bf16 v[92:95], v[182:185], v[154:157], v[92:95]
	s_or_b64 exec, exec, s[28:29]
	s_and_saveexec_b64 s[28:29], s[6:7]
	s_cbranch_execz .LBB0_269
.LBB0_275:
	ds_read_b128 v[154:157], v0 offset:34944
	ds_read_b128 v[170:173], v143 offset:128
	ds_read_b128 v[174:177], v143 offset:4480
	ds_read_b128 v[178:181], v143 offset:8832
	ds_read_b128 v[182:185], v143 offset:13184
	s_waitcnt lgkmcnt(3)
	v_mfma_f32_16x16x32_bf16 v[104:107], v[170:173], v[154:157], v[104:107]
	s_waitcnt lgkmcnt(2)
	v_mfma_f32_16x16x32_bf16 v[100:103], v[174:177], v[154:157], v[100:103]
	s_waitcnt lgkmcnt(1)
	v_mfma_f32_16x16x32_bf16 v[96:99], v[178:181], v[154:157], v[96:99]
	s_waitcnt lgkmcnt(0)
	v_mfma_f32_16x16x32_bf16 v[92:95], v[182:185], v[154:157], v[92:95]
	s_or_b64 exec, exec, s[28:29]
	s_and_saveexec_b64 s[28:29], s[8:9]
	s_cbranch_execnz .LBB0_270
	s_branch .LBB0_271

.LBB0_597:
	s_andn2_b64 vcc, exec, s[4:5]
	s_cbranch_vccnz .LBB0_623
	v_mov_b32_e32 v142, v201
	v_readlane_b32 s2, v253, 53
	s_waitcnt vmcnt(0)
	v_readlane_b32 s4, v252, 37
	s_add_u32 s6, s2, 0x1080000
	v_readlane_b32 s2, v253, 55
	v_readlane_b32 s5, v252, 38
	s_addc_u32 s7, s2, 0
	v_readfirstlane_b32 s2, v142
	s_andn2_b64 vcc, exec, s[4:5]
	s_barrier
	s_cbranch_vccnz .LBB0_622
	s_movk_i32 s4, 0x100
	v_cmp_gt_i32_e64 s[4:5], s4, v142
	v_mov_b32_e32 v3, 0
	s_and_saveexec_b64 s[8:9], s[4:5]
	s_cbranch_execz .LBB0_601
	v_readlane_b32 s10, v252, 61
	v_readlane_b32 s11, v252, 62
	s_nop 0
	v_add_u32_e32 v2, s10, v142
	v_ashrrev_i32_e32 v3, 31, v2
	v_readlane_b32 s10, v253, 50
	v_lshlrev_b64 v[2:3], 6, v[2:3]
	v_readlane_b32 s11, v253, 51
	s_nop 1
	v_lshl_add_u64 v[14:15], s[10:11], 0, v[2:3]
	global_load_dwordx4 v[160:163], v[14:15], off offset:32
	global_load_dwordx4 v[164:167], v[14:15], off offset:16
	global_load_dwordx4 v[168:171], v[14:15], off
	global_load_dwordx4 v[172:175], v[14:15], off offset:48

.LBB0_603:
	v_mov_b32_e32 v131, v1
	v_lshl_add_u64 v[8:9], s[10:11], 0, v[130:131]
	v_mov_b32_e32 v133, v1
	v_lshl_add_u64 v[10:11], s[10:11], 0, v[132:133]
	s_add_i32 m0, s27, 0x18000
	v_lshl_add_u64 v[8:9], v[8:9], 0, s[0:1]
	v_lshl_add_u64 v[12:13], s[12:13], 0, v[130:131]
	s_waitcnt vmcnt(2)
	s_barrier
	global_load_lds_dwordx4 v[8:9], off
	v_lshl_add_u64 v[8:9], v[10:11], 0, s[0:1]
	s_add_i32 m0, s27, 0x1a000
	s_add_i32 s31, s27, 0x8000
	s_add_i32 s33, s27, 0xa000
	v_lshl_add_u64 v[14:15], s[12:13], 0, v[132:133]
	global_load_lds_dwordx4 v[8:9], off
	v_lshl_add_u64 v[8:9], v[12:13], 0, s[0:1]
	s_mov_b32 m0, s31
	s_add_u32 s10, s10, 0x40080
	global_load_lds_dwordx4 v[8:9], off
	v_lshl_add_u64 v[8:9], v[14:15], 0, s[0:1]
	s_mov_b32 m0, s33
	s_addc_u32 s11, s11, 0
	global_load_lds_dwordx4 v[8:9], off
	s_add_i32 m0, s27, 0x1c000
	v_lshl_add_u64 v[8:9], s[10:11], 0, v[130:131]
	global_load_lds_dwordx4 v[8:9], off
	v_lshl_add_u64 v[8:9], s[10:11], 0, v[132:133]
	s_add_i32 m0, s27, 0x1e000
	s_nop 0
	global_load_lds_dwordx4 v[8:9], off
	s_waitcnt vmcnt(6)
	s_barrier
	s_and_saveexec_b64 s[10:11], s[4:5]
	v_lshl_add_u32 v8, v142, 2, 0
	v_add_u32_e32 v8, 0x21040, v8
	v_add_f32_e32 v176, v168, v169
	v_add_f32_e32 v177, v170, v171
	v_add_f32_e32 v176, v176, v177
	v_add_f32_e32 v177, v164, v165
	v_add_f32_e32 v178, v166, v167
	v_add_f32_e32 v177, v177, v178
	v_add_f32_e32 v176, v176, v177
	v_add_f32_e32 v177, v160, v161
	v_add_f32_e32 v178, v162, v163
	v_add_f32_e32 v177, v177, v178
	v_add_f32_e32 v176, v176, v177
	v_add_f32_e32 v177, v172, v173
	v_add_f32_e32 v178, v174, v175
	v_add_f32_e32 v177, v177, v178
	v_add_f32_e32 v176, v176, v177
	s_mov_b32 s98, 0x800000
	v_fmamk_f32 v176, v176, 0x3a800000, v241
	v_mul_f32_e32 v177, 0x4b800000, v176
	v_cmp_gt_f32_e32 vcc, s98, v176
	s_nop 1
	v_cndmask_b32_e32 v176, v176, v177, vcc
	v_rsq_f32_e32 v176, v176
	s_nop 0
	v_mul_f32_e32 v177, 0x45800000, v176
	v_cndmask_b32_e32 v3, v176, v177, vcc
	ds_write_b32 v8, v3
	s_or_b64 exec, exec, s[10:11]
	v_lshrrev_b32_e32 v8, 1, v142
	v_and_b32_e32 v3, 15, v142
	v_and_b32_e32 v8, 24, v8
	v_lshl_or_b32 v143, s14, 6, v3
	v_lshlrev_b32_e32 v9, 1, v8
	v_lshl_or_b32 v3, v3, 6, v9
	v_lshlrev_b32_e32 v9, 2, v143
	s_lshl_b32 s10, s14, 13
	v_and_b32_e32 v10, 32, v9
	v_bitop3_b32 v10, v3, s10, v10 bitop3:0xde
	s_lshl_b32 s10, s15, 5
	s_and_b32 s14, s10, 0x60
	v_lshlrev_b32_e32 v11, 2, v142
	s_lshl_b32 s10, s14, 7
	v_and_b32_e32 v12, 32, v11
	v_bitop3_b32 v144, v3, s10, v12 bitop3:0xde
	v_lshlrev_b32_e32 v3, 14, v4
	s_add_i32 s12, 0, 0x21040
	v_readlane_b32 s16, v253, 46
	v_and_b32_e32 v3, 0xffff8000, v3
	s_cmpk_lt_u32 s2, 0x100
	v_readlane_b32 s18, v253, 48
	v_lshl_add_u32 v0, v0, 11, v3
	v_and_b32_e32 v3, 1, v4
	v_add_u32_e32 v145, s12, v11
	s_cselect_b64 s[10:11], -1, 0
	v_add_u32_e32 v146, s12, v9
	v_readlane_b32 s19, v253, 49
	s_add_u32 s12, s18, 0x5040080
	v_lshl_or_b32 v0, v3, 6, v0
	s_addc_u32 s13, s19, 0
	v_lshl_add_u32 v0, v5, 1, v0
	v_lshl_add_u64 v[134:135], s[12:13], 0, v[0:1]
	v_lshlrev_b32_e32 v0, 14, v2
	v_and_b32_e32 v0, 0xffff8000, v0
	v_lshl_add_u32 v0, v6, 11, v0
	v_and_b32_e32 v2, 1, v2
	v_lshl_or_b32 v0, v2, 6, v0
	v_lshl_add_u32 v0, v7, 1, v0
	v_readlane_b32 s2, v253, 52
	v_lshl_add_u64 v[136:137], s[12:13], 0, v[0:1]
	s_add_u32 s2, s18, s2
	v_readlane_b32 s12, v253, 54
	s_addc_u32 s12, s19, s12
	s_add_u32 s34, s2, 0x1080100
	v_readlane_b32 s40, v252, 54
	v_readlane_b32 s41, v252, 55
	v_readlane_b32 s20, v252, 56
	v_readlane_b32 s22, v252, 63
	s_addc_u32 s35, s12, 0
	s_mov_b32 s36, 0
	v_add_u32_e32 v147, 0, v10
	s_lshl_b32 s2, s14, 1
	v_lshlrev_b32_e32 v0, 1, v8
	v_readlane_b32 s21, v252, 57
	v_readlane_b32 s23, v253, 0
	v_readlane_b32 s37, v251, 0
	s_mov_b32 s39, s40
	s_mov_b32 s38, s41
	v_readlane_b32 s17, v253, 47
	s_branch .LBB0_608
	s_nop 0
	s_nop 0
	s_nop 0
	s_nop 0
	s_nop 0
	s_nop 0
	s_nop 0

.LBB0_659:
	v_mov_b32_e32 v70, v201
	v_readlane_b32 s4, v253, 56
	v_ashrrev_i32_e32 v71, 6, v70
	v_and_b32_e32 v73, 63, v70
	v_lshlrev_b32_e32 v6, 2, v71
	v_lshlrev_b32_e32 v0, 4, v73
	v_readlane_b32 s5, v253, 57
	v_ashrrev_i32_e32 v7, 31, v6
	v_lshlrev_b64 v[2:3], 11, v[6:7]
	v_lshl_add_u64 v[8:9], s[4:5], 0, v[0:1]
	v_lshl_add_u64 v[10:11], v[8:9], 0, v[2:3]
	s_barrier
	global_load_dwordx4 v[102:105], v[10:11], off
	global_load_dwordx4 v[106:109], v[10:11], off offset:1024
	v_lshrrev_b32_e32 v26, 1, v70
	v_and_b32_e32 v28, 15, v70
	v_and_b32_e32 v26, 24, v26
	v_lshl_or_b32 v50, v71, 7, v26
	v_lshlrev_b32_e32 v26, 11, v28
	v_add_u32_e32 v28, s2, v28
	v_mov_b32_e32 v27, v1
	v_ashrrev_i32_e32 v29, 31, v28
	v_lshl_add_u64 v[26:27], s[4:5], 0, v[26:27]
	s_mov_b64 s[4:5], 0x8000
	v_lshlrev_b64 v[28:29], 11, v[28:29]
	v_ashrrev_i32_e32 v51, 31, v50
	v_lshl_add_u64 v[54:55], v[26:27], 0, s[4:5]
	v_lshl_add_u64 v[30:31], s[6:7], 0, v[28:29]
	v_lshlrev_b64 v[32:33], 1, v[50:51]
	v_lshl_add_u64 v[52:53], v[26:27], 0, v[32:33]
	v_lshl_add_u64 v[34:35], v[54:55], 0, v[32:33]
	v_lshl_add_u64 v[56:57], v[30:31], 0, v[32:33]
	v_or_b32_e32 v38, 32, v50
	v_ashrrev_i32_e32 v39, 31, v38
	v_lshl_add_u64 v[38:39], v[38:39], 1, v[54:55]
	v_or_b32_e32 v46, 64, v50
	v_ashrrev_i32_e32 v47, 31, v46
	v_lshl_add_u64 v[46:47], v[46:47], 1, v[54:55]
	v_or_b32_e32 v74, 0x60, v50
	v_ashrrev_i32_e32 v75, 31, v74
	v_lshl_add_u64 v[54:55], v[74:75], 1, v[54:55]
	v_or_b32_e32 v2, 1, v6
	v_ashrrev_i32_e32 v3, 31, v2
	v_lshlrev_b64 v[2:3], 11, v[2:3]
	v_lshl_add_u64 v[2:3], v[8:9], 0, v[2:3]
	global_load_dwordx4 v[22:25], v[2:3], off
	global_load_dwordx4 v[18:21], v[2:3], off offset:1024
	v_or_b32_e32 v2, 2, v6
	v_ashrrev_i32_e32 v3, 31, v2
	v_lshlrev_b64 v[2:3], 11, v[2:3]
	v_lshl_add_u64 v[2:3], v[8:9], 0, v[2:3]
	global_load_dwordx4 v[14:17], v[2:3], off
	global_load_dwordx4 v[10:13], v[2:3], off offset:1024
	v_or_b32_e32 v2, 3, v6
	v_ashrrev_i32_e32 v3, 31, v2
	v_lshlrev_b64 v[2:3], 11, v[2:3]
	v_lshl_add_u64 v[2:3], v[8:9], 0, v[2:3]
	global_load_dwordx4 v[6:9], v[2:3], off
	s_nop 0
	global_load_dwordx4 v[2:5], v[2:3], off offset:1024
	s_nop 0
	global_load_dwordx4 v[26:29], v[52:53], off
	global_load_dwordx4 v[58:61], v[34:35], off
	global_load_dwordx4 v[30:33], v[52:53], off offset:64
	s_nop 0
	global_load_dwordx4 v[34:37], v[56:57], off
	global_load_dwordx4 v[62:65], v[38:39], off
	global_load_dwordx4 v[42:45], v[56:57], off offset:64
	s_waitcnt vmcnt(2)
	v_lshlrev_b32_e32 v110, 16, v102
	v_and_b32_e32 v111, 0xffff0000, v102
	v_mul_f32_e32 v111, v111, v111
	v_fmac_f32_e32 v111, v110, v110
	v_lshlrev_b32_e32 v110, 16, v103
	v_fmac_f32_e32 v111, v110, v110
	v_and_b32_e32 v110, 0xffff0000, v103
	v_fmac_f32_e32 v111, v110, v110
	v_lshlrev_b32_e32 v110, 16, v104
	v_fmac_f32_e32 v111, v110, v110
	v_and_b32_e32 v110, 0xffff0000, v104
	v_fmac_f32_e32 v111, v110, v110
	v_lshlrev_b32_e32 v110, 16, v105
	v_fmac_f32_e32 v111, v110, v110
	v_and_b32_e32 v110, 0xffff0000, v105
	v_fmac_f32_e32 v111, v110, v110
	v_lshlrev_b32_e32 v110, 16, v106
	v_and_b32_e32 v112, 0xffff0000, v106
	v_mul_f32_e32 v112, v112, v112
	v_fmac_f32_e32 v112, v110, v110
	v_lshlrev_b32_e32 v110, 16, v107
	v_fmac_f32_e32 v112, v110, v110
	v_and_b32_e32 v110, 0xffff0000, v107
	v_fmac_f32_e32 v112, v110, v110
	v_lshlrev_b32_e32 v110, 16, v108
	v_fmac_f32_e32 v112, v110, v110
	v_and_b32_e32 v110, 0xffff0000, v108
	v_fmac_f32_e32 v112, v110, v110
	v_lshlrev_b32_e32 v110, 16, v109
	v_fmac_f32_e32 v112, v110, v110
	v_and_b32_e32 v110, 0xffff0000, v109
	v_fmac_f32_e32 v112, v110, v110
	v_add_f32_e32 v72, v111, v112
	v_mfma_f32_16x16x32_bf16 v[58:61], v[34:37], v[58:61], 0
	global_load_dwordx4 v[38:41], v[52:53], off offset:128
	global_load_dwordx4 v[66:69], v[46:47], off
	s_nop 0
	global_load_dwordx4 v[46:49], v[56:57], off offset:128
	s_nop 0
	global_load_dwordx4 v[50:53], v[52:53], off offset:192
	s_nop 0
	global_load_dwordx4 v[74:77], v[54:55], off
	s_nop 0
	global_load_dwordx4 v[54:57], v[56:57], off offset:192
	s_waitcnt vmcnt(6)
	v_mfma_f32_16x16x32_bf16 v[58:61], v[42:45], v[62:65], v[58:61]
	v_and_b32_e32 v62, 64, v243
	v_xor_b32_e32 v63, 16, v243
	v_xor_b32_e32 v64, 8, v243
	s_waitcnt vmcnt(3)
	v_mfma_f32_16x16x32_bf16 v[58:61], v[46:49], v[66:69], v[58:61]
	v_add_u32_e32 v67, 64, v62
	v_xor_b32_e32 v62, 32, v243
	v_cmp_lt_i32_e32 vcc, v62, v67
	v_xor_b32_e32 v65, 4, v243
	v_xor_b32_e32 v66, 2, v243
	v_cndmask_b32_e32 v62, v243, v62, vcc
	v_lshlrev_b32_e32 v62, 2, v62
	ds_bpermute_b32 v69, v62, v72
	v_cmp_lt_i32_e32 vcc, v63, v67
	v_xor_b32_e32 v68, 1, v243
	s_waitcnt vmcnt(0)
	v_mfma_f32_16x16x32_bf16 v[58:61], v[54:57], v[74:77], v[58:61]
	v_cndmask_b32_e32 v63, v243, v63, vcc
	v_lshlrev_b32_e32 v63, 2, v63
	s_waitcnt lgkmcnt(0)
	v_add_f32_e32 v69, v72, v69
	ds_bpermute_b32 v72, v63, v69
	v_cmp_lt_i32_e32 vcc, v64, v67
	s_waitcnt lgkmcnt(0)
	v_add_f32_e32 v69, v69, v72
	v_cndmask_b32_e32 v64, v243, v64, vcc
	v_lshlrev_b32_e32 v64, 2, v64
	ds_bpermute_b32 v72, v64, v69
	v_cmp_lt_i32_e32 vcc, v65, v67
	s_waitcnt lgkmcnt(0)
	v_add_f32_e32 v69, v69, v72
	v_cndmask_b32_e32 v65, v243, v65, vcc
	v_lshlrev_b32_e32 v65, 2, v65
	ds_bpermute_b32 v72, v65, v69
	v_cmp_lt_i32_e32 vcc, v66, v67
	s_waitcnt lgkmcnt(0)
	v_add_f32_e32 v69, v69, v72
	v_cndmask_b32_e32 v66, v243, v66, vcc
	v_lshlrev_b32_e32 v66, 2, v66
	ds_bpermute_b32 v72, v66, v69
	v_cmp_lt_i32_e32 vcc, v68, v67
	s_waitcnt lgkmcnt(0)
	v_add_f32_e32 v69, v69, v72
	v_cndmask_b32_e32 v67, v243, v68, vcc
	v_lshlrev_b32_e32 v67, 2, v67
	ds_bpermute_b32 v72, v67, v69
	v_lshlrev_b32_e32 v68, 4, v71
	v_cmp_eq_u32_e32 vcc, 0, v73
	v_add_u32_e32 v68, 0, v68
	s_and_saveexec_b64 s[8:9], vcc
	s_cbranch_execz .LBB0_661
	s_waitcnt lgkmcnt(0)
	v_add_f32_e32 v69, v69, v72
	v_fmamk_f32 v69, v69, 0x3a800000, v241
	s_mov_b32 s4, 0x800000
	v_mul_f32_e32 v72, 0x4b800000, v69
	v_cmp_gt_f32_e64 s[4:5], s4, v69
	s_nop 1
	v_cndmask_b32_e64 v69, v69, v72, s[4:5]
	v_rsq_f32_e32 v69, v69
	s_nop 0
	v_mul_f32_e32 v72, 0x45800000, v69
	v_cndmask_b32_e64 v69, v69, v72, s[4:5]
	ds_write_b32 v68, v69 offset:16384

.LBB0_674:
	s_nop 0
	v_readlane_b32 s4, v254, 14
	v_readlane_b32 s5, v254, 15
	s_andn2_b64 vcc, exec, s[4:5]
	s_cbranch_vccnz .LBB0_700
	v_readlane_b32 s2, v254, 13
	s_cmp_eq_u32 s2, 0
	v_mov_b32_e32 v146, v201
	s_cselect_b32 s12, 0, 0x1780000
	v_readlane_b32 s2, v253, 53
	s_waitcnt vmcnt(0)
	v_readlane_b32 s4, v252, 41
	s_add_u32 s6, s2, s12
	v_readlane_b32 s2, v253, 55
	v_readlane_b32 s5, v252, 42
	s_addc_u32 s7, s2, 0
	v_readfirstlane_b32 s13, v146
	s_andn2_b64 vcc, exec, s[4:5]
	s_barrier
	s_cbranch_vccnz .LBB0_699
	s_movk_i32 s2, 0x100
	v_cmp_gt_i32_e64 s[40:41], s2, v146
	v_mov_b32_e32 v4, 0
	s_and_saveexec_b64 s[4:5], s[40:41]
	s_cbranch_execz .LBB0_678
	v_readlane_b32 s8, v253, 14
	v_readlane_b32 s9, v253, 15
	s_mov_b32 s2, 0x800000
	v_add_u32_e32 v2, s8, v146
	v_ashrrev_i32_e32 v3, 31, v2
	v_readlane_b32 s8, v253, 50
	v_lshlrev_b64 v[2:3], 6, v[2:3]
	v_readlane_b32 s9, v253, 51
	s_nop 1
	v_lshl_add_u64 v[14:15], s[8:9], 0, v[2:3]
	global_load_dwordx4 v[168:171], v[14:15], off
	global_load_dwordx4 v[164:167], v[14:15], off offset:16
	global_load_dwordx4 v[160:163], v[14:15], off offset:32
	global_load_dwordx4 v[172:175], v[14:15], off offset:48

.LBB0_680:
	v_lshl_add_u64 v[10:11], s[8:9], 0, v[0:1]
	v_mov_b32_e32 v131, v1
	v_lshl_add_u64 v[12:13], s[8:9], 0, v[130:131]
	s_add_i32 m0, s24, 0x18000
	v_lshl_add_u64 v[10:11], v[10:11], 0, s[0:1]
	v_lshl_add_u64 v[14:15], s[10:11], 0, v[0:1]
	s_waitcnt vmcnt(2)
	s_barrier
	global_load_lds_dwordx4 v[10:11], off
	v_lshl_add_u64 v[10:11], v[12:13], 0, s[0:1]
	s_add_i32 m0, s24, 0x1a000
	s_add_i32 s28, s24, 0x8000
	s_add_i32 s29, s24, 0xa000
	v_lshl_add_u64 v[16:17], s[10:11], 0, v[130:131]
	global_load_lds_dwordx4 v[10:11], off
	v_lshl_add_u64 v[10:11], v[14:15], 0, s[0:1]
	s_mov_b32 m0, s28
	s_add_u32 s8, s8, 0x40080
	global_load_lds_dwordx4 v[10:11], off
	v_lshl_add_u64 v[10:11], v[16:17], 0, s[0:1]
	s_mov_b32 m0, s29
	s_addc_u32 s9, s9, 0
	global_load_lds_dwordx4 v[10:11], off
	s_add_i32 m0, s24, 0x1c000
	v_lshl_add_u64 v[10:11], s[8:9], 0, v[0:1]
	global_load_lds_dwordx4 v[10:11], off
	v_lshl_add_u64 v[10:11], s[8:9], 0, v[130:131]
	s_add_i32 m0, s24, 0x1e000
	s_nop 0
	global_load_lds_dwordx4 v[10:11], off
	s_waitcnt vmcnt(6)
	s_barrier
	s_and_saveexec_b64 s[8:9], s[40:41]
	v_lshl_add_u32 v9, v146, 2, 0
	v_add_u32_e32 v9, 0x21040, v9
	v_add_f32_e32 v176, v168, v169
	v_add_f32_e32 v177, v170, v171
	v_add_f32_e32 v176, v176, v177
	v_add_f32_e32 v177, v164, v165
	v_add_f32_e32 v178, v166, v167
	v_add_f32_e32 v177, v177, v178
	v_add_f32_e32 v176, v176, v177
	v_add_f32_e32 v177, v160, v161
	v_add_f32_e32 v178, v162, v163
	v_add_f32_e32 v177, v177, v178
	v_add_f32_e32 v176, v176, v177
	v_add_f32_e32 v177, v172, v173
	v_add_f32_e32 v178, v174, v175
	v_add_f32_e32 v177, v177, v178
	v_add_f32_e32 v176, v176, v177
	s_mov_b32 s98, 0x800000
	v_fmamk_f32 v176, v176, 0x3a800000, v241
	v_mul_f32_e32 v177, 0x4b800000, v176
	v_cmp_gt_f32_e32 vcc, s98, v176
	s_nop 1
	v_cndmask_b32_e32 v176, v176, v177, vcc
	v_rsq_f32_e32 v176, v176
	s_nop 0
	v_mul_f32_e32 v177, 0x45800000, v176
	v_cndmask_b32_e32 v4, v176, v177, vcc
	ds_write_b32 v9, v4
	s_or_b64 exec, exec, s[8:9]
	v_lshrrev_b32_e32 v9, 1, v146
	v_and_b32_e32 v4, 15, v146
	v_and_b32_e32 v9, 24, v9
	v_lshl_or_b32 v147, s14, 6, v4
	v_lshlrev_b32_e32 v10, 1, v9
	v_lshl_or_b32 v4, v4, 6, v10
	v_lshlrev_b32_e32 v10, 2, v147
	s_lshl_b32 s8, s14, 13
	v_and_b32_e32 v11, 32, v10
	v_bitop3_b32 v11, v4, s8, v11 bitop3:0xde
	s_lshl_b32 s8, s15, 5
	s_and_b32 s10, s8, 0x60
	v_lshlrev_b32_e32 v12, 2, v146
	s_lshl_b32 s8, s10, 7
	v_and_b32_e32 v13, 32, v12
	v_bitop3_b32 v148, v4, s8, v13 bitop3:0xde
	v_lshlrev_b32_e32 v4, 14, v5
	v_and_b32_e32 v4, 0xffff8000, v4
	v_lshl_add_u32 v3, v3, 11, v4
	v_and_b32_e32 v4, 1, v5
	v_lshl_or_b32 v3, v4, 6, v3
	v_lshl_add_u32 v4, v6, 1, v3
	v_lshlrev_b32_e32 v3, 14, v2
	s_add_i32 s11, 0, 0x21040
	v_readlane_b32 s16, v253, 46
	v_and_b32_e32 v3, 0xffff8000, v3
	s_cmpk_lt_u32 s13, 0x100
	v_readlane_b32 s18, v253, 48
	v_lshl_add_u32 v3, v7, 11, v3
	v_and_b32_e32 v2, 1, v2
	s_cselect_b64 s[8:9], -1, 0
	v_or_b32_e32 v151, s10, v9
	v_readlane_b32 s19, v253, 49
	s_add_u32 s10, s18, 0x5040080
	v_lshl_or_b32 v2, v2, 6, v3
	v_add_u32_e32 v149, s11, v12
	v_add_u32_e32 v150, s11, v10
	s_addc_u32 s11, s19, 0
	v_mov_b32_e32 v5, v1
	v_lshl_add_u32 v2, v8, 1, v2
	v_mov_b32_e32 v3, v1
	v_lshl_add_u64 v[132:133], s[10:11], 0, v[4:5]
	v_lshl_add_u64 v[134:135], s[10:11], 0, v[2:3]
	v_readlane_b32 s10, v253, 52
	s_add_u32 s10, s12, s10
	v_readlane_b32 s11, v253, 54
	s_addc_u32 s11, 0, s11
	s_add_u32 s10, s18, s10
	s_addc_u32 s11, s19, s11
	s_add_u32 s30, s10, 0x100
	v_readlane_b32 s37, v253, 3
	v_readlane_b32 s38, v253, 4
	v_readlane_b32 s18, v253, 5
	v_readlane_b32 s20, v253, 16
	s_addc_u32 s31, s11, 0
	s_mov_b32 s33, 0
	v_add_u32_e32 v152, 0, v11
	v_readlane_b32 s19, v253, 6
	v_readlane_b32 s21, v253, 17
	v_readlane_b32 s34, v251, 0
	s_mov_b32 s36, s37
	s_mov_b32 s35, s38
	v_readlane_b32 s17, v253, 47
	s_branch .LBB0_685
	s_nop 0
	s_nop 0
	s_nop 0
	s_nop 0
	s_nop 0
	s_nop 0
	s_nop 0

.LBB0_704:
	v_mov_b32_e32 v62, v201
	v_readlane_b32 s8, v253, 56
	v_ashrrev_i32_e32 v63, 6, v62
	v_and_b32_e32 v64, 63, v62
	v_lshlrev_b32_e32 v6, 2, v63
	v_lshlrev_b32_e32 v0, 4, v64
	v_readlane_b32 s9, v253, 57
	v_ashrrev_i32_e32 v7, 31, v6
	v_lshlrev_b64 v[2:3], 11, v[6:7]
	v_lshl_add_u64 v[8:9], s[8:9], 0, v[0:1]
	v_lshl_add_u64 v[10:11], v[8:9], 0, v[2:3]
	s_barrier
	global_load_dwordx4 v[102:105], v[10:11], off
	global_load_dwordx4 v[106:109], v[10:11], off offset:1024
	v_or_b32_e32 v58, 1, v6
	s_and_b32 s4, s2, 0xffffff00
	s_and_b32 s5, s10, 0x70
	v_ashrrev_i32_e32 v59, 31, v58
	s_or_b32 s4, s4, s5
	v_or_b32_e32 v60, 2, v6
	v_and_b32_e32 v28, 15, v62
	v_ashrrev_i32_e32 v61, 31, v60
	v_lshrrev_b32_e32 v0, 1, v62
	v_lshlrev_b64 v[2:3], 11, v[58:59]
	v_and_b32_e32 v0, 24, v0
	v_lshl_add_u64 v[2:3], v[8:9], 0, v[2:3]
	v_lshl_or_b32 v50, v63, 7, v0
	v_lshlrev_b32_e32 v0, 11, v28
	v_or_b32_e32 v28, s4, v28
	global_load_dwordx4 v[22:25], v[2:3], off
	global_load_dwordx4 v[18:21], v[2:3], off offset:1024
	v_lshlrev_b64 v[2:3], 11, v[60:61]
	v_ashrrev_i32_e32 v29, 31, v28
	v_lshl_add_u64 v[2:3], v[8:9], 0, v[2:3]
	v_lshlrev_b64 v[30:31], 11, v[28:29]
	v_or_b32_e32 v28, 0x80, v28
	global_load_dwordx4 v[14:17], v[2:3], off
	global_load_dwordx4 v[10:13], v[2:3], off offset:1024
	v_or_b32_e32 v2, 3, v6
	v_ashrrev_i32_e32 v29, 31, v28
	v_ashrrev_i32_e32 v3, 31, v2
	v_lshlrev_b64 v[28:29], 11, v[28:29]
	v_ashrrev_i32_e32 v51, 31, v50
	v_lshlrev_b64 v[2:3], 11, v[2:3]
	v_lshl_add_u64 v[34:35], s[6:7], 0, v[30:31]
	v_lshl_add_u64 v[28:29], s[6:7], 0, v[28:29]
	v_lshlrev_b64 v[36:37], 1, v[50:51]
	v_lshl_add_u64 v[2:3], v[8:9], 0, v[2:3]
	v_lshl_add_u64 v[90:91], v[34:35], 0, v[36:37]
	v_lshl_add_u64 v[94:95], v[28:29], 0, v[36:37]
	global_load_dwordx4 v[6:9], v[2:3], off
	s_nop 0
	global_load_dwordx4 v[2:5], v[2:3], off offset:1024
	v_lshl_add_u64 v[26:27], s[8:9], 0, v[0:1]
	global_load_dwordx4 v[66:69], v[90:91], off
	global_load_dwordx4 v[70:73], v[94:95], off
	s_mov_b64 s[8:9], 0x8000
	v_lshl_add_u64 v[54:55], v[26:27], 0, s[8:9]
	v_lshl_add_u64 v[52:53], v[26:27], 0, v[36:37]
	global_load_dwordx4 v[38:41], v[52:53], off
	v_lshl_add_u64 v[26:27], v[54:55], 0, v[36:37]
	global_load_dwordx4 v[30:33], v[26:27], off
	v_or_b32_e32 v26, 32, v50
	v_ashrrev_i32_e32 v27, 31, v26
	v_lshl_add_u64 v[26:27], v[26:27], 1, v[54:55]
	global_load_dwordx4 v[34:37], v[52:53], off offset:64
	s_nop 0
	global_load_dwordx4 v[26:29], v[26:27], off
	s_nop 0
	global_load_dwordx4 v[74:77], v[90:91], off offset:64
	global_load_dwordx4 v[78:81], v[94:95], off offset:64
	v_or_b32_e32 v42, 64, v50
	v_ashrrev_i32_e32 v43, 31, v42
	v_lshl_add_u64 v[42:43], v[42:43], 1, v[54:55]
	global_load_dwordx4 v[46:49], v[52:53], off offset:128
	s_nop 0
	global_load_dwordx4 v[42:45], v[42:43], off
	s_nop 0
	global_load_dwordx4 v[82:85], v[90:91], off offset:128
	global_load_dwordx4 v[86:89], v[94:95], off offset:128
	v_or_b32_e32 v56, 0x60, v50
	v_ashrrev_i32_e32 v57, 31, v56
	v_lshl_add_u64 v[54:55], v[56:57], 1, v[54:55]
	global_load_dwordx4 v[50:53], v[52:53], off offset:192
	s_nop 0
	global_load_dwordx4 v[54:57], v[54:55], off
	s_nop 0
	global_load_dwordx4 v[90:93], v[90:91], off offset:192
	s_nop 0
	global_load_dwordx4 v[94:97], v[94:95], off offset:192
	v_and_b32_e32 v0, 64, v243
	s_waitcnt vmcnt(13)
	v_lshlrev_b32_e32 v110, 16, v102
	v_and_b32_e32 v111, 0xffff0000, v102
	v_mul_f32_e32 v111, v111, v111
	v_fmac_f32_e32 v111, v110, v110
	v_lshlrev_b32_e32 v110, 16, v103
	v_fmac_f32_e32 v111, v110, v110
	v_and_b32_e32 v110, 0xffff0000, v103
	v_fmac_f32_e32 v111, v110, v110
	v_lshlrev_b32_e32 v110, 16, v104
	v_fmac_f32_e32 v111, v110, v110
	v_and_b32_e32 v110, 0xffff0000, v104
	v_fmac_f32_e32 v111, v110, v110
	v_lshlrev_b32_e32 v110, 16, v105
	v_fmac_f32_e32 v111, v110, v110
	v_and_b32_e32 v110, 0xffff0000, v105
	v_fmac_f32_e32 v111, v110, v110
	v_lshlrev_b32_e32 v110, 16, v106
	v_and_b32_e32 v112, 0xffff0000, v106
	v_mul_f32_e32 v112, v112, v112
	v_fmac_f32_e32 v112, v110, v110
	v_lshlrev_b32_e32 v110, 16, v107
	v_fmac_f32_e32 v112, v110, v110
	v_and_b32_e32 v110, 0xffff0000, v107
	v_fmac_f32_e32 v112, v110, v110
	v_lshlrev_b32_e32 v110, 16, v108
	v_fmac_f32_e32 v112, v110, v110
	v_and_b32_e32 v110, 0xffff0000, v108
	v_fmac_f32_e32 v112, v110, v110
	v_lshlrev_b32_e32 v110, 16, v109
	v_fmac_f32_e32 v112, v110, v110
	v_and_b32_e32 v110, 0xffff0000, v109
	v_fmac_f32_e32 v112, v110, v110
	v_add_f32_e32 v65, v111, v112
	v_mfma_f32_16x16x32_bf16 v[98:101], v[66:69], v[38:41], 0
	v_mfma_f32_16x16x32_bf16 v[38:41], v[70:73], v[38:41], 0
	s_waitcnt vmcnt(12)
	v_mfma_f32_16x16x32_bf16 v[66:69], v[66:69], v[30:33], 0
	v_mfma_f32_16x16x32_bf16 v[30:33], v[70:73], v[30:33], 0
	s_waitcnt vmcnt(9)
	v_mfma_f32_16x16x32_bf16 v[70:73], v[74:77], v[34:37], v[98:101]
	s_waitcnt vmcnt(8)
	v_mfma_f32_16x16x32_bf16 v[34:37], v[78:81], v[34:37], v[38:41]
	v_mfma_f32_16x16x32_bf16 v[66:69], v[74:77], v[26:29], v[66:69]
	v_mfma_f32_16x16x32_bf16 v[26:29], v[78:81], v[26:29], v[30:33]
	s_waitcnt vmcnt(5)
	v_mfma_f32_16x16x32_bf16 v[30:33], v[82:85], v[46:49], v[70:73]
	s_waitcnt vmcnt(4)
	v_mfma_f32_16x16x32_bf16 v[34:37], v[86:89], v[46:49], v[34:37]
	v_add_u32_e32 v46, 64, v0
	v_xor_b32_e32 v0, 32, v243
	v_cmp_lt_i32_e32 vcc, v0, v46
	v_mfma_f32_16x16x32_bf16 v[38:41], v[82:85], v[42:45], v[66:69]
	v_xor_b32_e32 v47, 1, v243
	v_cndmask_b32_e32 v0, v243, v0, vcc
	v_lshlrev_b32_e32 v0, 2, v0
	v_mfma_f32_16x16x32_bf16 v[42:45], v[86:89], v[42:45], v[26:29]
	ds_bpermute_b32 v48, v0, v65
	s_waitcnt lgkmcnt(0)
	v_add_f32_e32 v48, v65, v48
	s_waitcnt vmcnt(1)
	v_mfma_f32_16x16x32_bf16 v[26:29], v[90:93], v[50:53], v[30:33]
	v_mfma_f32_16x16x32_bf16 v[30:33], v[90:93], v[54:57], v[38:41]
	s_waitcnt vmcnt(0)
	v_mfma_f32_16x16x32_bf16 v[38:41], v[94:97], v[54:57], v[42:45]
	s_nop 2
	v_xor_b32_e32 v42, 16, v243
	v_cmp_lt_i32_e32 vcc, v42, v46
	v_xor_b32_e32 v43, 8, v243
	v_xor_b32_e32 v44, 4, v243
	v_cndmask_b32_e32 v42, v243, v42, vcc
	v_lshlrev_b32_e32 v42, 2, v42
	ds_bpermute_b32 v49, v42, v48
	v_cmp_lt_i32_e32 vcc, v43, v46
	v_xor_b32_e32 v45, 2, v243
	v_mfma_f32_16x16x32_bf16 v[34:37], v[94:97], v[50:53], v[34:37]
	v_cndmask_b32_e32 v43, v243, v43, vcc
	v_lshlrev_b32_e32 v43, 2, v43
	s_waitcnt lgkmcnt(0)
	v_add_f32_e32 v48, v48, v49
	ds_bpermute_b32 v49, v43, v48
	v_cmp_lt_i32_e32 vcc, v44, v46
	s_waitcnt lgkmcnt(0)
	v_add_f32_e32 v48, v48, v49
	v_cndmask_b32_e32 v44, v243, v44, vcc
	v_lshlrev_b32_e32 v44, 2, v44
	ds_bpermute_b32 v49, v44, v48
	v_cmp_lt_i32_e32 vcc, v45, v46
	s_waitcnt lgkmcnt(0)
	v_add_f32_e32 v48, v48, v49
	v_cndmask_b32_e32 v45, v243, v45, vcc
	v_lshlrev_b32_e32 v45, 2, v45
	ds_bpermute_b32 v49, v45, v48
	v_cmp_lt_i32_e32 vcc, v47, v46
	s_waitcnt lgkmcnt(0)
	v_add_f32_e32 v48, v48, v49
	v_cndmask_b32_e32 v46, v243, v47, vcc
	v_lshlrev_b32_e32 v46, 2, v46
	ds_bpermute_b32 v49, v46, v48
	v_lshlrev_b32_e32 v47, 4, v63
	v_cmp_eq_u32_e32 vcc, 0, v64
	v_add_u32_e32 v47, 0, v47
	s_and_saveexec_b64 s[8:9], vcc
	s_cbranch_execz .LBB0_706
	s_waitcnt lgkmcnt(0)
	v_add_f32_e32 v48, v48, v49
	v_fmamk_f32 v48, v48, 0x3a800000, v241
	s_mov_b32 s4, 0x800000
	v_mul_f32_e32 v49, 0x4b800000, v48
	v_cmp_gt_f32_e64 s[4:5], s4, v48
	s_nop 1
	v_cndmask_b32_e64 v48, v48, v49, s[4:5]
	v_rsq_f32_e32 v48, v48
	s_nop 0
	v_mul_f32_e32 v49, 0x45800000, v48
	v_cndmask_b32_e64 v48, v48, v49, s[4:5]
	ds_write_b32 v47, v48 offset:32768

.LBB0_710:
	s_or_b64 exec, exec, s[8:9]
	v_lshlrev_b32_e32 v10, 16, v6
	v_and_b32_e32 v6, 0xffff0000, v6
	v_mul_f32_e32 v6, v6, v6
	v_fmac_f32_e32 v6, v10, v10
	v_lshlrev_b32_e32 v10, 16, v7
	v_fmac_f32_e32 v6, v10, v10
	v_and_b32_e32 v7, 0xffff0000, v7
	v_fmac_f32_e32 v6, v7, v7
	v_lshlrev_b32_e32 v7, 16, v8
	v_fmac_f32_e32 v6, v7, v7
	v_and_b32_e32 v7, 0xffff0000, v8
	v_fmac_f32_e32 v6, v7, v7
	v_lshlrev_b32_e32 v7, 16, v9
	v_fmac_f32_e32 v6, v7, v7
	v_and_b32_e32 v7, 0xffff0000, v9
	v_fmac_f32_e32 v6, v7, v7
	v_lshlrev_b32_e32 v7, 16, v2
	v_and_b32_e32 v2, 0xffff0000, v2
	v_mul_f32_e32 v2, v2, v2
	v_fmac_f32_e32 v2, v7, v7
	v_lshlrev_b32_e32 v7, 16, v3
	v_fmac_f32_e32 v2, v7, v7
	v_and_b32_e32 v3, 0xffff0000, v3
	v_fmac_f32_e32 v2, v3, v3
	v_lshlrev_b32_e32 v3, 16, v4
	v_fmac_f32_e32 v2, v3, v3
	v_and_b32_e32 v3, 0xffff0000, v4
	v_fmac_f32_e32 v2, v3, v3
	v_lshlrev_b32_e32 v3, 16, v5
	v_fmac_f32_e32 v2, v3, v3
	v_and_b32_e32 v3, 0xffff0000, v5
	v_fmac_f32_e32 v2, v3, v3
	v_add_f32_e32 v2, v6, v2
	ds_bpermute_b32 v0, v0, v2
	s_waitcnt lgkmcnt(0)
	v_add_f32_e32 v0, v2, v0
	ds_bpermute_b32 v2, v42, v0
	s_waitcnt lgkmcnt(0)
	v_add_f32_e32 v0, v0, v2
	ds_bpermute_b32 v2, v43, v0
	s_waitcnt lgkmcnt(0)
	v_add_f32_e32 v0, v0, v2
	ds_bpermute_b32 v2, v44, v0
	s_waitcnt lgkmcnt(0)
	v_add_f32_e32 v0, v0, v2
	ds_bpermute_b32 v2, v45, v0
	s_waitcnt lgkmcnt(0)
	v_add_f32_e32 v0, v0, v2
	ds_bpermute_b32 v2, v46, v0
	s_and_saveexec_b64 s[4:5], vcc
	s_cbranch_execz .LBB0_703
	s_waitcnt lgkmcnt(0)
	v_add_f32_e32 v0, v0, v2
	v_fmamk_f32 v0, v0, 0x3a800000, v241
	s_mov_b32 s8, 0x800000
	v_mul_f32_e32 v2, 0x4b800000, v0
	v_cmp_gt_f32_e32 vcc, s8, v0
	s_nop 1
	v_cndmask_b32_e32 v0, v0, v2, vcc
	v_rsq_f32_e32 v0, v0
	s_nop 0
	v_mul_f32_e32 v2, 0x45800000, v0
	v_cndmask_b32_e32 v0, v0, v2, vcc
	ds_write_b32 v47, v0 offset:32780
	s_branch .LBB0_703
	s_nop 0
	s_nop 0
